# v57 + attention V^T staging: in-quad 4x4 dword transpose (v_cndmask dpp) + byte transpose (v_perm_b32), 8 ds_write_b32 per thread instead of 32 ds_write_b8
# speedup vs baseline: 1.0355x; 1.0021x over previous
; #define LAS __attribute__((address_space(3)))
; __device__ __forceinline__ void attn_load(const unsigned char* QKV, const AttnUnitGeo& u, int tid, int w, int fr, int quad, u32x4 (&kr)[2], u32x4 (&vr)[2], long& q0, long& q1) {
;     const size_t hs = (size_t)SEQ * 64;
;     const unsigned char* qh = QKV + ((size_t)(0 * BATCH + u.b) * 12 + u.head) * hs; const unsigned char* kh = qh + (size_t)BATCH * 12 * hs; const unsigned char* vh = kh + (size_t)BATCH * 12 * hs;
;     const int p0 = (u.r << (11 - u.dsh)) + u.nb * 128;
; #pragma unroll
;     for (int i = 0; i < 2; ++i) { const int c = tid + NTHREADS * i, row = c >> 2, part = c & 3;
;         kr[i] = (u32x4){0u, 0u, 0u, 0u}; if (u.nb > 0 || row >= 128) kr[i] = *(const u32x4*)(kh + (size_t)(p0 - 128 + row) * 64 + part * 16); }
; __device__ __forceinline__ void attn_phase(const Params& p, LAS unsigned char* lds, int tid, int G, int bid) {
;     ...
;         for (int i = 0; i < 2; ++i) { const int c = tid + NTHREADS * i, row = c >> 2, part = c & 3; *(LAS u32x4*)(lds + row * KS_PITCH + part * 16) = kr[i]; }
; #pragma unroll
;         for (int i = 0; i < 2; ++i) { const int c = tid + NTHREADS * i, part = c >> 8, row = c & 255; const u32x4 v = vr[i];
;             LAS unsigned char* vt = lds + VT_OFF + (part * 16) * VT_PITCH + row;
; #pragma unroll
;             for (int e = 0; e < 16; ++e) vt[e * VT_PITCH] = (unsigned char)((v[e >> 2] >> (8 * (e & 3))) & 0xffu); }
.LBB0_271:
	ds_write_b128 v93, v[4:7]
	ds_write_b128 v166, v[0:3]
	v_mov_b32_e32 v213, 0x5010400
	v_mov_b32_e32 v214, 0x7030602
	v_mov_b32_e32 v215, 0x5040100
	v_mov_b32_e32 v216, 0x7060302
	v_and_b32_e32 v217, 3, v167
	v_mul_u32_u24_e32 v217, 0x43f, v217
	v_add_u32_e32 v218, v217, v167
	v_add_u32_e32 v219, v217, v168
	s_mov_b32 vcc_lo, 0xaaaaaaaa
	s_mov_b32 vcc_hi, 0xaaaaaaaa
	v_cndmask_b32_dpp v221, v16, v17, vcc quad_perm:[1,0,3,2] row_mask:0xf bank_mask:0xf
	v_cndmask_b32_dpp v223, v18, v19, vcc quad_perm:[1,0,3,2] row_mask:0xf bank_mask:0xf
	v_cndmask_b32_dpp v225, v12, v13, vcc quad_perm:[1,0,3,2] row_mask:0xf bank_mask:0xf
	v_cndmask_b32_dpp v227, v14, v15, vcc quad_perm:[1,0,3,2] row_mask:0xf bank_mask:0xf
	s_mov_b32 vcc_lo, 0x55555555
	s_mov_b32 vcc_hi, 0x55555555
	v_cndmask_b32_dpp v220, v17, v16, vcc quad_perm:[1,0,3,2] row_mask:0xf bank_mask:0xf
	v_cndmask_b32_dpp v222, v19, v18, vcc quad_perm:[1,0,3,2] row_mask:0xf bank_mask:0xf
	v_cndmask_b32_dpp v224, v13, v12, vcc quad_perm:[1,0,3,2] row_mask:0xf bank_mask:0xf
	v_cndmask_b32_dpp v226, v15, v14, vcc quad_perm:[1,0,3,2] row_mask:0xf bank_mask:0xf
	s_mov_b32 vcc_lo, 0xcccccccc
	s_mov_b32 vcc_hi, 0xcccccccc
	v_cndmask_b32_dpp v230, v220, v222, vcc quad_perm:[2,3,0,1] row_mask:0xf bank_mask:0xf
	v_cndmask_b32_dpp v231, v221, v223, vcc quad_perm:[2,3,0,1] row_mask:0xf bank_mask:0xf
	v_cndmask_b32_dpp v234, v224, v226, vcc quad_perm:[2,3,0,1] row_mask:0xf bank_mask:0xf
	v_cndmask_b32_dpp v235, v225, v227, vcc quad_perm:[2,3,0,1] row_mask:0xf bank_mask:0xf
	s_mov_b32 vcc_lo, 0x33333333
	s_mov_b32 vcc_hi, 0x33333333
	v_cndmask_b32_dpp v228, v222, v220, vcc quad_perm:[2,3,0,1] row_mask:0xf bank_mask:0xf
	v_cndmask_b32_dpp v229, v223, v221, vcc quad_perm:[2,3,0,1] row_mask:0xf bank_mask:0xf
	v_cndmask_b32_dpp v232, v226, v224, vcc quad_perm:[2,3,0,1] row_mask:0xf bank_mask:0xf
	v_cndmask_b32_dpp v233, v227, v225, vcc quad_perm:[2,3,0,1] row_mask:0xf bank_mask:0xf
	v_perm_b32 v236, v229, v228, v213
	v_perm_b32 v237, v231, v230, v213
	v_perm_b32 v238, v229, v228, v214
	v_perm_b32 v239, v231, v230, v214
	v_perm_b32 v240, v237, v236, v215
	v_perm_b32 v241, v237, v236, v216
	v_perm_b32 v242, v239, v238, v215
	v_perm_b32 v243, v239, v238, v216
	ds_write_b32 v218, v240 offset:20480
	ds_write_b32 v218, v241 offset:20752
	ds_write_b32 v218, v242 offset:21024
	ds_write_b32 v218, v243 offset:21296
	v_perm_b32 v236, v233, v232, v213
	v_perm_b32 v237, v235, v234, v213
	v_perm_b32 v238, v233, v232, v214
	v_perm_b32 v239, v235, v234, v214
	v_perm_b32 v244, v237, v236, v215
	v_perm_b32 v245, v237, v236, v216
	v_perm_b32 v246, v239, v238, v215
	v_perm_b32 v247, v239, v238, v216
	ds_write_b32 v219, v244 offset:20480
	ds_write_b32 v219, v245 offset:20752
	ds_write_b32 v219, v246 offset:21024
	ds_write_b32 v219, v247 offset:21296
	s_add_i32 s10, s11, s98
	s_cmpk_gt_i32 s10, 0xbff
	s_cselect_b64 s[82:83], -1, 0
	s_and_b64 vcc, exec, s[82:83]
	s_waitcnt lgkmcnt(0)
	s_barrier
	s_cbranch_vccnz .LBB0_279
	s_mul_hi_i32 s0, s10, 0x2aaaaaab
	s_lshr_b32 s1, s0, 31
	s_ashr_i32 s0, s0, 5
	s_add_i32 s0, s0, s1
	s_mul_i32 s1, s0, 0xffffff40
	s_add_i32 s1, s10, s1
	s_ashr_i32 s1, s1, 6
	s_bfe_u32 s4, s10, 0x20004
	s_mul_i32 s0, s0, 12
	s_lshl_b32 s6, s1, 1
	s_lshl_b32 s1, s1, 2
	s_or_b32 s0, s0, s4
	s_add_i32 s0, s0, s1
	s_and_b32 s5, s10, 15
	s_ashr_i32 s1, s0, 31
	s_lshr_b32 s7, s5, s6
	s_lshl_b64 s[0:1], s[0:1], 17
	v_readlane_b32 s12, v250, 18
	v_readlane_b32 s13, v250, 19
	s_add_u32 s0, s12, s0
	s_addc_u32 s1, s13, s1
	s_sub_i32 s4, 11, s6
	s_lshl_b32 s4, s5, s4
	s_and_b32 s84, s4, 0x7fe
	s_lshl_b32 s4, s7, 7
	s_add_i32 s84, s84, s4
	s_add_i32 s85, s84, 0xffffff80
	v_lshl_add_u64 v[0:1], s[0:1], 0, v[84:85]
	s_mov_b64 s[4:5], 0x1800000
	s_cmp_lg_u32 s7, 0
	v_readlane_b32 s6, v250, 26
	v_mov_b32_e32 v2, v8
	v_mov_b32_e32 v3, v8
	v_lshl_add_u64 v[10:11], v[0:1], 0, s[4:5]
	s_cselect_b64 s[4:5], -1, 0
	v_readlane_b32 s7, v250, 27
	v_mov_b32_e32 v0, 0
	v_mov_b32_e32 v1, v8
	v_mov_b64_e32 v[6:7], v[2:3]
	s_or_b64 vcc, s[6:7], s[4:5]
	v_mov_b64_e32 v[4:5], v[0:1]
	s_and_saveexec_b64 s[6:7], vcc
	s_cbranch_execz .LBB0_274
	v_add_u32_e32 v4, s85, v120
	v_ashrrev_i32_e32 v5, 31, v4
	v_lshlrev_b64 v[4:5], 6, v[4:5]
	v_lshl_add_u64 v[4:5], v[10:11], 0, v[4:5]
	global_load_dwordx4 v[4:7], v[4:5], off
